# same as previous (pair-level LDS handshakes in S5 pass 2) with a larger bound on the handshake spin
# baseline (speedup 1.0000x reference)
.Lp8_poll2:
	s_add_u32 vcc_lo, vcc_lo, 1
	s_cmpk_gt_u32 vcc_lo, 0x4e20
	s_cbranch_scc1 .Lp8_poll2_done
	ds_read_b32 v230, v203 offset:32
	s_waitcnt lgkmcnt(0)
	s_nop 0
	v_readfirstlane_b32 s94, v230
	s_nop 3
	s_cmp_ge_u32 s94, s85
	s_cbranch_scc1 .Lp8_poll2_done
	s_sleep 1
	s_branch .Lp8_poll2

.Lp8_poll1:
	s_add_u32 vcc_lo, vcc_lo, 1
	s_cmpk_gt_u32 vcc_lo, 0x4e20
	s_cbranch_scc1 .Lp8_poll1_done
	ds_read_b32 v230, v203
	s_waitcnt lgkmcnt(0)
	s_nop 0
	v_readfirstlane_b32 s94, v230
	s_nop 3
	s_cmp_ge_u32 s94, s85
	s_cbranch_scc1 .Lp8_poll1_done
	s_sleep 1
	s_branch .Lp8_poll1
